# grid barrier: the last XCD leader bumps every XCD generation word itself (no top-generation relay hop); workgroups invalidate L1 before polling
# speedup vs baseline: 1.0143x; 1.0143x over previous
; DI unsigned xb_ld(unsigned* p)              { return __hip_atomic_load(p, __ATOMIC_RELAXED, __HIP_MEMORY_SCOPE_AGENT); }
; DI unsigned xb_add(unsigned* p, unsigned v) { return __hip_atomic_fetch_add(p, v, __ATOMIC_RELAXED, __HIP_MEMORY_SCOPE_AGENT); }
; #define XB_SPIN(cond, bar) do { unsigned _sp = 0; while (cond) { __builtin_amdgcn_s_sleep(1); \
;     if ((++_sp & 255u) == 0u) { if (xb_ld(&(bar)[XB_TMO])) break; if (_sp > XB_SPIN_CAP) { atomicAdd(&(bar)[XB_TMO], 1u); break; } } } } while (0)
; DI void xcd_barrier(const XcdBarrier& b) {
;     ...
;         const unsigned old = xb_add(&bar[XB_XSUB(b.x)], 1u);
;         const unsigned gen = old / nloc;
;         if (old + 1u == (gen + 1u) * nloc) {
;             __builtin_amdgcn_fence(__ATOMIC_RELEASE, "agent");
;             asm volatile("s_waitcnt vmcnt(0)" ::: "memory");
;             const unsigned og = xb_add(&bar[XB_TOP], 1u);
;             const unsigned tg = og / nx;
;             if (og + 1u == (tg + 1u) * nx) xb_add(&bar[XB_TOPGEN], 1u);
;             else XB_SPIN(xb_ld(&bar[XB_TOPGEN]) == tg, bar);
.LBB0_155:
	s_andn2_saveexec_b64 s[12:13], s[36:37]
	s_cbranch_execz .LBB0_175
	s_mov_b64 s[36:37], exec
	s_mov_b32 s100, 0
	buffer_wbl2 sc1
	s_waitcnt lgkmcnt(0)
	s_waitcnt vmcnt(0)
	v_mbcnt_lo_u32_b32 v0, s36, 0
	v_mbcnt_hi_u32_b32 v0, s37, v0
	v_cmp_eq_u32_e32 vcc, 0, v0
	s_and_saveexec_b64 s[38:39], vcc
	s_cbranch_execz .LBB0_158
	s_bcnt1_i32_b64 s12, s[36:37]
	v_mov_b32_e32 v3, s12
	v_readlane_b32 s12, v252, 12
	v_readlane_b32 s13, v252, 13
	s_nop 4
	global_atomic_add v3, v1, v3, s[12:13] sc0
.LBB0_158:
	s_or_b64 exec, exec, s[38:39]
	v_cvt_f32_u32_e32 v4, v2
	s_waitcnt vmcnt(0)
	v_readfirstlane_b32 s12, v3
	s_mov_b64 s[38:39], -1
	v_rcp_iflag_f32_e32 v4, v4
	v_add_u32_e32 v0, s12, v0
	v_add_u32_e32 v5, 1, v0
	v_readlane_b32 s12, v252, 14
	v_mul_f32_e32 v3, 0x4f7ffffe, v4
	v_cvt_u32_f32_e32 v3, v3
	v_sub_u32_e32 v4, 0, v2
	v_readlane_b32 s13, v252, 15
	v_mul_lo_u32 v4, v4, v3
	v_mul_hi_u32 v4, v3, v4
	v_add_u32_e32 v3, v3, v4
	v_mul_hi_u32 v3, v0, v3
	v_mul_lo_u32 v4, v3, v2
	v_sub_u32_e32 v0, v0, v4
	v_add_u32_e32 v6, 1, v3
	v_cmp_ge_u32_e32 vcc, v0, v2
	v_sub_u32_e32 v4, v0, v2
	s_nop 0
	v_cndmask_b32_e32 v3, v3, v6, vcc
	v_cndmask_b32_e32 v0, v0, v4, vcc
	v_add_u32_e32 v4, 1, v3
	v_cmp_ge_u32_e32 vcc, v0, v2
	s_nop 1
	v_cndmask_b32_e32 v0, v3, v4, vcc
	v_mul_lo_u32 v3, v2, v0
	v_add_u32_e32 v2, v3, v2
	v_cmp_ne_u32_e32 vcc, v5, v2
	v_mov_b64_e32 v[2:3], s[12:13]
	s_and_saveexec_b64 s[36:37], vcc
	s_cbranch_execz .LBB0_170
	s_mov_b32 s100, 1
	v_readlane_b32 s12, v252, 14
	v_readlane_b32 s13, v252, 15
	s_mov_b64 s[40:41], 0
	s_nop 3
	global_load_dword v2, v1, s[12:13] sc1
	s_waitcnt vmcnt(0)
	v_cmp_eq_u32_e32 vcc, v2, v0
	s_and_saveexec_b64 s[38:39], vcc
	s_cbranch_execz .LBB0_169
	s_mov_b32 s12, 1
	s_branch .LBB0_162

; DI unsigned xb_ld(unsigned* p)              { return __hip_atomic_load(p, __ATOMIC_RELAXED, __HIP_MEMORY_SCOPE_AGENT); }
; DI unsigned xb_add(unsigned* p, unsigned v) { return __hip_atomic_fetch_add(p, v, __ATOMIC_RELAXED, __HIP_MEMORY_SCOPE_AGENT); }
; #define XB_SPIN(cond, bar) do { unsigned _sp = 0; while (cond) { __builtin_amdgcn_s_sleep(1); \
;     if ((++_sp & 255u) == 0u) { if (xb_ld(&(bar)[XB_TMO])) break; if (_sp > XB_SPIN_CAP) { atomicAdd(&(bar)[XB_TMO], 1u); break; } } } } while (0)
; DI void xcd_barrier(const XcdBarrier& b) {
;     ...
;             if (og + 1u == (tg + 1u) * nx) xb_add(&bar[XB_TOPGEN], 1u);
;             else XB_SPIN(xb_ld(&bar[XB_TOPGEN]) == tg, bar);
;             __builtin_amdgcn_fence(__ATOMIC_ACQUIRE, "agent");
;             xb_add(&bar[XB_XGEN(b.x)], 1u);
;             asm volatile("s_waitcnt vmcnt(0)" ::: "memory");
.LBB0_170:
	s_or_b64 exec, exec, s[36:37]
	s_and_saveexec_b64 s[36:37], s[38:39]
	s_cbranch_execz .LBB0_172
	global_atomic_add v[2:3], v250, off
	s_cmp_lg_u32 s100, 0
	s_cbranch_scc1 .Lxb_skip_1
	v_add_co_u32_e32 v4, vcc, 0xffffef00, v2
	s_nop 1
	v_addc_co_u32_e32 v5, vcc, -1, v3, vcc
	global_atomic_add v[4:5], v250, off
	global_atomic_add v[4:5], v250, off offset:256
	global_atomic_add v[4:5], v250, off offset:512
	global_atomic_add v[4:5], v250, off offset:768
	global_atomic_add v[4:5], v250, off offset:1024
	global_atomic_add v[4:5], v250, off offset:1280
	global_atomic_add v[4:5], v250, off offset:1536
	global_atomic_add v[4:5], v250, off offset:1792
	global_atomic_add v[4:5], v250, off offset:2048
	global_atomic_add v[4:5], v250, off offset:2304
	global_atomic_add v[4:5], v250, off offset:2560
	global_atomic_add v[4:5], v250, off offset:2816
	global_atomic_add v[4:5], v250, off offset:3072
	global_atomic_add v[4:5], v250, off offset:3328
	global_atomic_add v[4:5], v250, off offset:3584
	global_atomic_add v[4:5], v250, off offset:3840
.Lxb_skip_1:
.LBB0_172:
	s_or_b64 exec, exec, s[36:37]
	s_mov_b64 s[36:37], exec
	v_mbcnt_lo_u32_b32 v0, s36, 0
	v_mbcnt_hi_u32_b32 v0, s37, v0
	v_cmp_eq_u32_e32 vcc, 0, v0
	s_waitcnt vmcnt(0)
	buffer_inv sc1
	s_and_saveexec_b64 s[38:39], vcc
	s_cbranch_execz .LBB0_174
	s_bcnt1_i32_b64 s12, s[36:37]
	v_mov_b32_e32 v0, s12
	v_readlane_b32 s12, v252, 10
	v_readlane_b32 s13, v252, 11
	s_nop 4

; DI unsigned xb_ld(unsigned* p)              { return __hip_atomic_load(p, __ATOMIC_RELAXED, __HIP_MEMORY_SCOPE_AGENT); }
; DI unsigned xb_add(unsigned* p, unsigned v) { return __hip_atomic_fetch_add(p, v, __ATOMIC_RELAXED, __HIP_MEMORY_SCOPE_AGENT); }
; #define XB_SPIN(cond, bar) do { unsigned _sp = 0; while (cond) { __builtin_amdgcn_s_sleep(1); \
;     if ((++_sp & 255u) == 0u) { if (xb_ld(&(bar)[XB_TMO])) break; if (_sp > XB_SPIN_CAP) { atomicAdd(&(bar)[XB_TMO], 1u); break; } } } } while (0)
; DI void xcd_barrier(const XcdBarrier& b) {
;     ...
;         if (old + 1u == (gen + 1u) * nloc) {
;             __builtin_amdgcn_fence(__ATOMIC_RELEASE, "agent");
;             asm volatile("s_waitcnt vmcnt(0)" ::: "memory");
;             const unsigned og = xb_add(&bar[XB_TOP], 1u);
;             const unsigned tg = og / nx;
;             if (og + 1u == (tg + 1u) * nx) xb_add(&bar[XB_TOPGEN], 1u);
;             else XB_SPIN(xb_ld(&bar[XB_TOPGEN]) == tg, bar);
.LBB0_413:
	s_or_b64 exec, exec, s[38:39]
	s_waitcnt vmcnt(0)
	v_readfirstlane_b32 s12, v3
	v_sub_u32_e32 v4, 0, v2
	s_mov_b64 s[38:39], -1
	v_add_u32_e32 v3, s12, v0
	v_cvt_f32_u32_e32 v0, v2
	v_readlane_b32 s12, v252, 14
	v_readlane_b32 s13, v252, 15
	v_rcp_iflag_f32_e32 v0, v0
	s_nop 0
	v_mul_f32_e32 v0, 0x4f7ffffe, v0
	v_cvt_u32_f32_e32 v0, v0
	v_mul_lo_u32 v4, v4, v0
	v_mul_hi_u32 v4, v0, v4
	v_add_u32_e32 v0, v0, v4
	v_mul_hi_u32 v0, v3, v0
	v_mul_lo_u32 v4, v0, v2
	v_sub_u32_e32 v4, v3, v4
	v_cmp_ge_u32_e32 vcc, v4, v2
	v_add_u32_e32 v5, 1, v0
	v_add_u32_e32 v3, 1, v3
	v_cndmask_b32_e32 v0, v0, v5, vcc
	v_sub_u32_e32 v5, v4, v2
	v_cndmask_b32_e32 v4, v4, v5, vcc
	v_cmp_ge_u32_e32 vcc, v4, v2
	v_add_u32_e32 v4, 1, v0
	s_nop 0
	v_cndmask_b32_e32 v0, v0, v4, vcc
	v_mul_lo_u32 v4, v2, v0
	v_add_u32_e32 v2, v4, v2
	v_cmp_ne_u32_e32 vcc, v3, v2
	v_mov_b64_e32 v[2:3], s[12:13]
	s_and_saveexec_b64 s[36:37], vcc
	s_cbranch_execz .LBB0_425
	s_mov_b32 s100, 1
	v_readlane_b32 s12, v252, 14
	v_readlane_b32 s13, v252, 15
	s_mov_b64 s[40:41], 0
	s_nop 3
	global_load_dword v2, v1, s[12:13] sc1
	s_waitcnt vmcnt(0)
	v_cmp_eq_u32_e32 vcc, v2, v0
	s_and_saveexec_b64 s[38:39], vcc
	s_cbranch_execz .LBB0_424
	s_mov_b32 s12, 1
	s_branch .LBB0_417

; DI unsigned xb_add(unsigned* p, unsigned v) { return __hip_atomic_fetch_add(p, v, __ATOMIC_RELAXED, __HIP_MEMORY_SCOPE_AGENT); }
; DI void xcd_barrier(const XcdBarrier& b) {
;     ...
;         const unsigned old = xb_add(&bar[XB_XSUB(b.x)], 1u);
;         const unsigned gen = old / nloc;
;         if (old + 1u == (gen + 1u) * nloc) {
;             __builtin_amdgcn_fence(__ATOMIC_RELEASE, "agent");
;             asm volatile("s_waitcnt vmcnt(0)" ::: "memory");
;             const unsigned og = xb_add(&bar[XB_TOP], 1u);
.LBB0_1496:
	s_mov_b64 s[36:37], exec
	s_mov_b32 s100, 0
	buffer_wbl2 sc1
	s_waitcnt lgkmcnt(0)
	s_waitcnt vmcnt(0)
	v_mbcnt_lo_u32_b32 v0, s36, 0
	v_mbcnt_hi_u32_b32 v0, s37, v0
	v_cmp_eq_u32_e32 vcc, 0, v0
	s_and_saveexec_b64 s[38:39], vcc
	s_cbranch_execz .LBB0_1498
	s_bcnt1_i32_b64 s12, s[36:37]
	v_mov_b32_e32 v3, s12
	v_readlane_b32 s12, v252, 12
	v_readlane_b32 s13, v252, 13
	s_nop 4
	global_atomic_add v3, v1, v3, s[12:13] sc0

; DI unsigned xb_add(unsigned* p, unsigned v) { return __hip_atomic_fetch_add(p, v, __ATOMIC_RELAXED, __HIP_MEMORY_SCOPE_AGENT); }
; DI void xcd_barrier(const XcdBarrier& b) {
;     ...
;             __builtin_amdgcn_fence(__ATOMIC_ACQUIRE, "agent");
;             xb_add(&bar[XB_XGEN(b.x)], 1u);
;             asm volatile("s_waitcnt vmcnt(0)" ::: "memory");
.Lxb_skip_13:
.LBB0_1512:
	s_or_b64 exec, exec, s[36:37]
	s_mov_b64 s[36:37], exec
	v_mbcnt_lo_u32_b32 v0, s36, 0
	v_mbcnt_hi_u32_b32 v0, s37, v0
	v_cmp_eq_u32_e32 vcc, 0, v0
	s_waitcnt vmcnt(0)
	buffer_inv sc1
	s_and_saveexec_b64 s[38:39], vcc
	s_cbranch_execnz .LBB0_1513
	s_getpc_b64 s[98:99]

; DI unsigned xb_add(unsigned* p, unsigned v) { return __hip_atomic_fetch_add(p, v, __ATOMIC_RELAXED, __HIP_MEMORY_SCOPE_AGENT); }
; DI void xcd_barrier(const XcdBarrier& b) {
;     ...
;             xb_add(&bar[XB_XGEN(b.x)], 1u);
.LBB0_1513:
	s_bcnt1_i32_b64 s12, s[36:37]
	v_mov_b32_e32 v0, s12
	v_readlane_b32 s12, v252, 10
	v_readlane_b32 s13, v252, 11
	s_nop 4
	s_getpc_b64 s[98:99]
